# merge phase rewritten with four pieces per thread in flight (on top of previous)
# baseline (speedup 1.0000x reference)
; __device__ __forceinline__ unsigned cvt_pk_bf16(float lo, float hi) { unsigned r; asm volatile("v_cvt_pk_bf16_f32 %0, %1, %2" : "=v"(r) : "v"(lo), "v"(hi)); return r; }
; __device__ __forceinline__ void merge_phase(const bf16_t* og, const float* lse, bf16_t* om) {
;     const size_t gt = (size_t)blockIdx.x * NTHREADS + threadIdx.x, NT = (size_t)gridDim.x * NTHREADS, tot = (size_t)MT * 96;
;     for (size_t i = gt; i < tot; i += NT) {
;         const size_t row = i / 96; const int c8 = (int)(i - row * 96), col = c8 * 8, g = col >> 8, hh = (col & 255) >> 6;
;         const float l0 = lse[row * 12 + hh], l1 = lse[row * 12 + 4 + hh], l2 = lse[row * 12 + 8 + hh];
;         const float m = fmaxf(fmaxf(l0, l1), l2), e0 = __expf(l0 - m), e1 = __expf(l1 - m), e2 = __expf(l2 - m);
;         const float al = (g == 0 ? e0 : (g == 1 ? e1 : e2)) / (e0 + e1 + e2);
;         const u32x4 w = *(const u32x4*)(og + row * AW + col); u32x4 o;
;         o.x = cvt_pk_bf16(__uint_as_float(w.x << 16) * al, __uint_as_float(w.x & 0xffff0000u) * al);
;         o.y = cvt_pk_bf16(__uint_as_float(w.y << 16) * al, __uint_as_float(w.y & 0xffff0000u) * al);
;         o.z = cvt_pk_bf16(__uint_as_float(w.z << 16) * al, __uint_as_float(w.z & 0xffff0000u) * al);
;         o.w = cvt_pk_bf16(__uint_as_float(w.w << 16) * al, __uint_as_float(w.w & 0xffff0000u) * al);
;         *(u32x4*)(om + row * AW + col) = o;
.LBB0_699:
	s_or_b64 exec, exec, s[28:29]
	s_load_dwordx2 s[6:7], s[0:1], 0xd0
	s_waitcnt lgkmcnt(0)
	s_barrier
	s_add_u32 s40, s6, 0x12140000
	s_addc_u32 s41, s7, 0
	s_sub_u32 s30, s40, 0x1860000
	s_subb_u32 s31, s41, 0
	s_add_u32 s32, s40, 0x1860000
	s_addc_u32 s33, s41, 0
	s_lshl_b32 s42, s66, 9
	s_lshl_b32 s44, s42, 2
	s_mov_b32 s45, 0xaaaaaaab
	s_mov_b32 s46, 1597439
	s_movk_i32 s47, 0x600
	v_mov_b32_e32 v18, v128
.Lmrg_loop:
	v_mov_b32_e32 v17, v18
	v_min_u32_e32 v0, s46, v17
	v_add_u32_e32 v17, s42, v17
	v_mul_hi_u32 v1, v0, s45
	v_lshrrev_b32_e32 v1, 6, v1
	v_mul_u32_u24_e32 v2, 0x60, v1
	v_sub_u32_e32 v2, v0, v2
	v_mul_lo_u32 v96, v1, s47
	v_lshl_add_u32 v96, v2, 4, v96
	v_mul_u32_u24_e32 v100, 48, v1
	v_bfe_u32 v3, v2, 3, 2
	v_lshl_add_u32 v100, v3, 2, v100
	v_lshrrev_b32_e32 v104, 5, v2
	global_load_dword v171, v100, s[32:33]
	global_load_dword v172, v100, s[32:33] offset:16
	global_load_dword v173, v100, s[32:33] offset:32
	global_load_dwordx4 v[196:199], v96, s[30:31]
	v_min_u32_e32 v0, s46, v17
	v_add_u32_e32 v17, s42, v17
	v_mul_hi_u32 v1, v0, s45
	v_lshrrev_b32_e32 v1, 6, v1
	v_mul_u32_u24_e32 v2, 0x60, v1
	v_sub_u32_e32 v2, v0, v2
	v_mul_lo_u32 v97, v1, s47
	v_lshl_add_u32 v97, v2, 4, v97
	v_mul_u32_u24_e32 v101, 48, v1
	v_bfe_u32 v3, v2, 3, 2
	v_lshl_add_u32 v101, v3, 2, v101
	v_lshrrev_b32_e32 v105, 5, v2
	global_load_dword v174, v101, s[32:33]
	global_load_dword v175, v101, s[32:33] offset:16
	global_load_dword v176, v101, s[32:33] offset:32
	global_load_dwordx4 v[200:203], v97, s[30:31]
	v_min_u32_e32 v0, s46, v17
	v_add_u32_e32 v17, s42, v17
	v_mul_hi_u32 v1, v0, s45
	v_lshrrev_b32_e32 v1, 6, v1
	v_mul_u32_u24_e32 v2, 0x60, v1
	v_sub_u32_e32 v2, v0, v2
	v_mul_lo_u32 v98, v1, s47
	v_lshl_add_u32 v98, v2, 4, v98
	v_mul_u32_u24_e32 v102, 48, v1
	v_bfe_u32 v3, v2, 3, 2
	v_lshl_add_u32 v102, v3, 2, v102
	v_lshrrev_b32_e32 v106, 5, v2
	global_load_dword v177, v102, s[32:33]
	global_load_dword v178, v102, s[32:33] offset:16
	global_load_dword v179, v102, s[32:33] offset:32
	global_load_dwordx4 v[208:211], v98, s[30:31]
	v_min_u32_e32 v0, s46, v17
	v_mul_hi_u32 v1, v0, s45
	v_lshrrev_b32_e32 v1, 6, v1
	v_mul_u32_u24_e32 v2, 0x60, v1
	v_sub_u32_e32 v2, v0, v2
	v_mul_lo_u32 v99, v1, s47
	v_lshl_add_u32 v99, v2, 4, v99
	v_mul_u32_u24_e32 v103, 48, v1
	v_bfe_u32 v3, v2, 3, 2
	v_lshl_add_u32 v103, v3, 2, v103
	v_lshrrev_b32_e32 v107, 5, v2
	global_load_dword v180, v103, s[32:33]
	global_load_dword v181, v103, s[32:33] offset:16
	global_load_dword v182, v103, s[32:33] offset:32
	global_load_dwordx4 v[212:215], v99, s[30:31]
	s_waitcnt vmcnt(12)
	v_max3_f32 v0, v171, v172, v173
	v_sub_f32_e32 v1, v171, v0
	v_sub_f32_e32 v2, v172, v0
	v_sub_f32_e32 v3, v173, v0
	v_mul_f32_e32 v1, 0x3fb8aa3b, v1
	v_mul_f32_e32 v2, 0x3fb8aa3b, v2
	v_mul_f32_e32 v3, 0x3fb8aa3b, v3
	v_exp_f32_e32 v2, v2
	v_exp_f32_e32 v3, v3
	v_exp_f32_e32 v1, v1
	v_cmp_eq_u32_e32 vcc, 1, v104
	s_nop 1
	v_cndmask_b32_e32 v4, v3, v2, vcc
	v_add_f32_e32 v5, v1, v2
	v_cmp_eq_u32_e32 vcc, 0, v104
	v_add_f32_e32 v5, v3, v5
	s_nop 0
	v_cndmask_b32_e32 v4, v4, v1, vcc
	v_div_scale_f32 v6, s[6:7], v5, v5, v4
	v_rcp_f32_e32 v7, v6
	v_div_scale_f32 v8, vcc, v4, v5, v4
	v_fma_f32 v9, -v6, v7, 1.0
	v_fmac_f32_e32 v7, v9, v7
	v_mul_f32_e32 v9, v8, v7
	v_fma_f32 v10, -v6, v9, v8
	v_fmac_f32_e32 v9, v10, v7
	v_fma_f32 v6, -v6, v9, v8
	v_div_fmas_f32 v6, v6, v7, v9
	v_div_fixup_f32 v4, v6, v5, v4
	v_lshlrev_b32_e32 v6, 16, v196
	v_and_b32_e32 v7, 0xffff0000, v196
	v_mul_f32_e32 v6, v4, v6
	v_mul_f32_e32 v7, v4, v7
	v_cvt_pk_bf16_f32 v196, v6, v7
	v_lshlrev_b32_e32 v6, 16, v197
	v_and_b32_e32 v7, 0xffff0000, v197
	v_mul_f32_e32 v6, v4, v6
	v_mul_f32_e32 v7, v4, v7
	v_cvt_pk_bf16_f32 v197, v6, v7
	v_lshlrev_b32_e32 v6, 16, v198
	v_and_b32_e32 v7, 0xffff0000, v198
	v_mul_f32_e32 v6, v4, v6
	v_mul_f32_e32 v7, v4, v7
	v_cvt_pk_bf16_f32 v198, v6, v7
	v_lshlrev_b32_e32 v6, 16, v199
	v_and_b32_e32 v7, 0xffff0000, v199
	v_mul_f32_e32 v6, v4, v6
	v_mul_f32_e32 v7, v4, v7
	v_cvt_pk_bf16_f32 v199, v6, v7
	global_store_dwordx4 v96, v[196:199], s[40:41]
	s_waitcnt vmcnt(9)
; __device__ __forceinline__ unsigned cvt_pk_bf16(float lo, float hi) { unsigned r; asm volatile("v_cvt_pk_bf16_f32 %0, %1, %2" : "=v"(r) : "v"(lo), "v"(hi)); return r; }
; __device__ __forceinline__ void merge_phase(const bf16_t* og, const float* lse, bf16_t* om) {
;     ...
;         const size_t row = i / 96; const int c8 = (int)(i - row * 96), col = c8 * 8, g = col >> 8, hh = (col & 255) >> 6;
;         const float l0 = lse[row * 12 + hh], l1 = lse[row * 12 + 4 + hh], l2 = lse[row * 12 + 8 + hh];
;         const float m = fmaxf(fmaxf(l0, l1), l2), e0 = __expf(l0 - m), e1 = __expf(l1 - m), e2 = __expf(l2 - m);
;         const float al = (g == 0 ? e0 : (g == 1 ? e1 : e2)) / (e0 + e1 + e2);
;         const u32x4 w = *(const u32x4*)(og + row * AW + col); u32x4 o;
;         o.x = cvt_pk_bf16(__uint_as_float(w.x << 16) * al, __uint_as_float(w.x & 0xffff0000u) * al);
;         o.y = cvt_pk_bf16(__uint_as_float(w.y << 16) * al, __uint_as_float(w.y & 0xffff0000u) * al);
;         o.z = cvt_pk_bf16(__uint_as_float(w.z << 16) * al, __uint_as_float(w.z & 0xffff0000u) * al);
;         o.w = cvt_pk_bf16(__uint_as_float(w.w << 16) * al, __uint_as_float(w.w & 0xffff0000u) * al);
;         *(u32x4*)(om + row * AW + col) = o;
;     }
	v_max3_f32 v0, v174, v175, v176
	v_sub_f32_e32 v1, v174, v0
	v_sub_f32_e32 v2, v175, v0
	v_sub_f32_e32 v3, v176, v0
	v_mul_f32_e32 v1, 0x3fb8aa3b, v1
	v_mul_f32_e32 v2, 0x3fb8aa3b, v2
	v_mul_f32_e32 v3, 0x3fb8aa3b, v3
	v_exp_f32_e32 v2, v2
	v_exp_f32_e32 v3, v3
	v_exp_f32_e32 v1, v1
	v_cmp_eq_u32_e32 vcc, 1, v105
	s_nop 1
	v_cndmask_b32_e32 v4, v3, v2, vcc
	v_add_f32_e32 v5, v1, v2
	v_cmp_eq_u32_e32 vcc, 0, v105
	v_add_f32_e32 v5, v3, v5
	s_nop 0
	v_cndmask_b32_e32 v4, v4, v1, vcc
	v_div_scale_f32 v6, s[6:7], v5, v5, v4
	v_rcp_f32_e32 v7, v6
	v_div_scale_f32 v8, vcc, v4, v5, v4
	v_fma_f32 v9, -v6, v7, 1.0
	v_fmac_f32_e32 v7, v9, v7
	v_mul_f32_e32 v9, v8, v7
	v_fma_f32 v10, -v6, v9, v8
	v_fmac_f32_e32 v9, v10, v7
	v_fma_f32 v6, -v6, v9, v8
	v_div_fmas_f32 v6, v6, v7, v9
	v_div_fixup_f32 v4, v6, v5, v4
	v_lshlrev_b32_e32 v6, 16, v200
	v_and_b32_e32 v7, 0xffff0000, v200
	v_mul_f32_e32 v6, v4, v6
	v_mul_f32_e32 v7, v4, v7
	v_cvt_pk_bf16_f32 v200, v6, v7
	v_lshlrev_b32_e32 v6, 16, v201
	v_and_b32_e32 v7, 0xffff0000, v201
	v_mul_f32_e32 v6, v4, v6
	v_mul_f32_e32 v7, v4, v7
	v_cvt_pk_bf16_f32 v201, v6, v7
	v_lshlrev_b32_e32 v6, 16, v202
	v_and_b32_e32 v7, 0xffff0000, v202
	v_mul_f32_e32 v6, v4, v6
	v_mul_f32_e32 v7, v4, v7
	v_cvt_pk_bf16_f32 v202, v6, v7
	v_lshlrev_b32_e32 v6, 16, v203
	v_and_b32_e32 v7, 0xffff0000, v203
	v_mul_f32_e32 v6, v4, v6
	v_mul_f32_e32 v7, v4, v7
	v_cvt_pk_bf16_f32 v203, v6, v7
	global_store_dwordx4 v97, v[200:203], s[40:41]
	s_waitcnt vmcnt(6)
	v_max3_f32 v0, v177, v178, v179
	v_sub_f32_e32 v1, v177, v0
	v_sub_f32_e32 v2, v178, v0
	v_sub_f32_e32 v3, v179, v0
	v_mul_f32_e32 v1, 0x3fb8aa3b, v1
	v_mul_f32_e32 v2, 0x3fb8aa3b, v2
	v_mul_f32_e32 v3, 0x3fb8aa3b, v3
	v_exp_f32_e32 v2, v2
	v_exp_f32_e32 v3, v3
	v_exp_f32_e32 v1, v1
	v_cmp_eq_u32_e32 vcc, 1, v106
	s_nop 1
	v_cndmask_b32_e32 v4, v3, v2, vcc
	v_add_f32_e32 v5, v1, v2
	v_cmp_eq_u32_e32 vcc, 0, v106
	v_add_f32_e32 v5, v3, v5
	s_nop 0
	v_cndmask_b32_e32 v4, v4, v1, vcc
	v_div_scale_f32 v6, s[6:7], v5, v5, v4
	v_rcp_f32_e32 v7, v6
	v_div_scale_f32 v8, vcc, v4, v5, v4
	v_fma_f32 v9, -v6, v7, 1.0
	v_fmac_f32_e32 v7, v9, v7
	v_mul_f32_e32 v9, v8, v7
	v_fma_f32 v10, -v6, v9, v8
	v_fmac_f32_e32 v9, v10, v7
	v_fma_f32 v6, -v6, v9, v8
	v_div_fmas_f32 v6, v6, v7, v9
	v_div_fixup_f32 v4, v6, v5, v4
	v_lshlrev_b32_e32 v6, 16, v208
	v_and_b32_e32 v7, 0xffff0000, v208
	v_mul_f32_e32 v6, v4, v6
	v_mul_f32_e32 v7, v4, v7
	v_cvt_pk_bf16_f32 v208, v6, v7
	v_lshlrev_b32_e32 v6, 16, v209
	v_and_b32_e32 v7, 0xffff0000, v209
	v_mul_f32_e32 v6, v4, v6
	v_mul_f32_e32 v7, v4, v7
	v_cvt_pk_bf16_f32 v209, v6, v7
	v_lshlrev_b32_e32 v6, 16, v210
	v_and_b32_e32 v7, 0xffff0000, v210
	v_mul_f32_e32 v6, v4, v6
	v_mul_f32_e32 v7, v4, v7
	v_cvt_pk_bf16_f32 v210, v6, v7
	v_lshlrev_b32_e32 v6, 16, v211
	v_and_b32_e32 v7, 0xffff0000, v211
	v_mul_f32_e32 v6, v4, v6
	v_mul_f32_e32 v7, v4, v7
	v_cvt_pk_bf16_f32 v211, v6, v7
	global_store_dwordx4 v98, v[208:211], s[40:41]
	s_waitcnt vmcnt(3)
	v_max3_f32 v0, v180, v181, v182
	v_sub_f32_e32 v1, v180, v0
	v_sub_f32_e32 v2, v181, v0
	v_sub_f32_e32 v3, v182, v0
	v_mul_f32_e32 v1, 0x3fb8aa3b, v1
	v_mul_f32_e32 v2, 0x3fb8aa3b, v2
	v_mul_f32_e32 v3, 0x3fb8aa3b, v3
	v_exp_f32_e32 v2, v2
	v_exp_f32_e32 v3, v3
	v_exp_f32_e32 v1, v1
	v_cmp_eq_u32_e32 vcc, 1, v107
	s_nop 1
	v_cndmask_b32_e32 v4, v3, v2, vcc
	v_add_f32_e32 v5, v1, v2
	v_cmp_eq_u32_e32 vcc, 0, v107
	v_add_f32_e32 v5, v3, v5
	s_nop 0
	v_cndmask_b32_e32 v4, v4, v1, vcc
	v_div_scale_f32 v6, s[6:7], v5, v5, v4
	v_rcp_f32_e32 v7, v6
	v_div_scale_f32 v8, vcc, v4, v5, v4
	v_fma_f32 v9, -v6, v7, 1.0
	v_fmac_f32_e32 v7, v9, v7
	v_mul_f32_e32 v9, v8, v7
	v_fma_f32 v10, -v6, v9, v8
	v_fmac_f32_e32 v9, v10, v7
	v_fma_f32 v6, -v6, v9, v8
	v_div_fmas_f32 v6, v6, v7, v9
	v_div_fixup_f32 v4, v6, v5, v4
	v_lshlrev_b32_e32 v6, 16, v212
	v_and_b32_e32 v7, 0xffff0000, v212
	v_mul_f32_e32 v6, v4, v6
	v_mul_f32_e32 v7, v4, v7
	v_cvt_pk_bf16_f32 v212, v6, v7
	v_lshlrev_b32_e32 v6, 16, v213
	v_and_b32_e32 v7, 0xffff0000, v213
	v_mul_f32_e32 v6, v4, v6
	v_mul_f32_e32 v7, v4, v7
	v_cvt_pk_bf16_f32 v213, v6, v7
	v_lshlrev_b32_e32 v6, 16, v214
	v_and_b32_e32 v7, 0xffff0000, v214
	v_mul_f32_e32 v6, v4, v6
	v_mul_f32_e32 v7, v4, v7
	v_cvt_pk_bf16_f32 v214, v6, v7
	v_lshlrev_b32_e32 v6, 16, v215
	v_and_b32_e32 v7, 0xffff0000, v215
	v_mul_f32_e32 v6, v4, v6
	v_mul_f32_e32 v7, v4, v7
	v_cvt_pk_bf16_f32 v215, v6, v7
	global_store_dwordx4 v99, v[212:215], s[40:41]
	v_add_u32_e32 v18, s44, v18
	v_cmp_ge_u32_e32 vcc, s46, v18
	s_cbranch_vccnz .Lmrg_loop
